# g2 step: next-chunk operand staging writes moved to right after the first barrier of the step
# speedup vs baseline: 1.0021x; 1.0013x over previous
.LBB0_135:
	ds_read_b128 v[72:75], v120
	ds_read_b128 v[76:79], v120 offset:64
	ds_read_b128 v[148:151], v121
	ds_read_b128 v[152:155], v121 offset:64
	ds_read_b128 v[80:83], v120 offset:128
	ds_read_b128 v[156:159], v120 offset:192
	ds_read_b128 v[160:163], v121 offset:128
	ds_read_b128 v[164:167], v121 offset:192
	ds_read_b64 v[168:169], v122 offset:62464
	s_setprio 1
	s_waitcnt lgkmcnt(6)
	v_mfma_f32_16x16x32_bf16 v[72:75], v[72:75], v[148:151], 0
	s_waitcnt lgkmcnt(5)
	v_mfma_f32_16x16x32_bf16 v[72:75], v[76:79], v[152:155], v[72:75]
	s_waitcnt lgkmcnt(0)
	v_lshlrev_b32_e32 v76, 16, v168
	v_and_b32_e32 v77, 0xffff0000, v168
	v_lshlrev_b32_e32 v78, 16, v169
	v_mfma_f32_16x16x32_bf16 v[72:75], v[80:83], v[160:163], v[72:75]
	v_and_b32_e32 v79, 0xffff0000, v169
	v_mfma_f32_16x16x32_bf16 v[72:75], v[156:159], v[164:167], v[72:75]
	s_nop 7
	v_pk_add_f32 v[72:73], v[76:77], v[72:73] neg_lo:[0,1] neg_hi:[0,1]
	v_pk_add_f32 v[74:75], v[78:79], v[74:75] neg_lo:[0,1] neg_hi:[0,1]
	v_cvt_pk_bf16_f32 v72, v72, v73
	v_cvt_pk_bf16_f32 v73, v74, v75
	ds_write_b64 v124, v[72:73]
	ds_read_b128 v[72:75], v120 offset:17408
	ds_read_b128 v[156:159], v120 offset:17472
	ds_read_b128 v[168:171], v120 offset:17536
	ds_read_b128 v[172:175], v120 offset:17600
	ds_read_b128 v[190:193], v125 offset:53248
	ds_read_b128 v[194:197], v125 offset:53312
	ds_read_b128 v[80:83], v126 offset:34816
	ds_read_b128 v[76:79], v126 offset:34880
	s_setprio 0
	s_waitcnt lgkmcnt(0)
	s_barrier
	s_waitcnt vmcnt(16)
	ds_write_b128 v127, v[0:3]
	s_waitcnt vmcnt(15)
	ds_write_b128 v128, v[4:7]
	s_waitcnt vmcnt(14)
	ds_write_b128 v129, v[8:11]
	s_waitcnt vmcnt(13)
	ds_write_b128 v130, v[12:15]
	s_waitcnt vmcnt(12)
	ds_write_b128 v131, v[16:19]
	s_waitcnt vmcnt(11)
	ds_write_b128 v132, v[20:23]
	s_waitcnt vmcnt(10)
	ds_write_b128 v133, v[28:31]
	s_and_saveexec_b64 s[24:25], s[4:5]
	s_cbranch_execz .LBB0_145
	s_waitcnt vmcnt(9)
	ds_write_b128 v134, v[32:35]
.LBB0_145:
	s_or_b64 exec, exec, s[24:25]
	s_setprio 1
	s_waitcnt lgkmcnt(7)
	v_mfma_f32_16x16x32_bf16 v[72:75], v[72:75], v[148:151], 0
	v_add_u32_e32 v149, v123, v119
	s_waitcnt lgkmcnt(6)
	v_mfma_f32_16x16x32_bf16 v[72:75], v[156:159], v[152:155], v[72:75]
	ds_read_b128 v[150:153], v149
	ds_read_b128 v[154:157], v149 offset:64
	ds_read_b128 v[216:219], v147
	ds_read_b128 v[220:223], v147 offset:64
	ds_read_b128 v[224:227], v147 offset:2304
	ds_read_b128 v[228:231], v147 offset:2368
	s_waitcnt lgkmcnt(7)
	v_mfma_f32_16x16x32_bf16 v[72:75], v[168:171], v[160:163], v[72:75]
	s_waitcnt lgkmcnt(6)
	v_mfma_f32_16x16x32_bf16 v[72:75], v[172:175], v[164:167], v[72:75]
	s_waitcnt lgkmcnt(5)
	v_mfma_f32_16x16x32_bf16 v[72:75], v[190:193], v[150:153], v[72:75]
	s_waitcnt lgkmcnt(4)
	v_mfma_f32_16x16x32_bf16 v[72:75], v[194:197], v[154:157], v[72:75]
	s_and_saveexec_b64 s[24:25], s[6:7]
	s_cbranch_execz .LBB0_139
	s_nop 5
	v_cvt_pk_bf16_f32 v72, v72, s0
	global_store_short v[110:111], v72, off offset:-4096
	s_or_b64 exec, exec, s[24:25]
	s_and_saveexec_b64 s[24:25], s[8:9]
	s_cbranch_execnz .LBB0_140

.LBB0_143:
	s_or_b64 exec, exec, s[24:25]
	s_nop 0
	v_pk_mul_f32 v[26:27], v[114:115], v[26:27] op_sel_hi:[0,1]
	v_pk_mul_f32 v[24:25], v[114:115], v[24:25] op_sel_hi:[0,1]
	s_waitcnt lgkmcnt(3)
	s_nop 0
	v_mfma_f32_16x16x32_bf16 v[24:27], v[80:83], v[216:219], v[24:27]
	s_nop 0
	s_waitcnt lgkmcnt(2)
	v_mfma_f32_16x16x32_bf16 v[72:75], v[76:79], v[220:223], v[24:27]
	s_nop 4
	v_mul_f32_e64 v26, v114, v38
	v_mul_f32_e64 v27, v114, v39
	s_nop 0
	v_cvt_pk_bf16_f32 v24, v72, v73
	v_cvt_pk_bf16_f32 v25, v74, v75
	ds_write_b64 v145, v[24:25]
	v_pk_mul_f32 v[24:25], v[114:115], v[36:37] op_sel_hi:[0,1]
	s_nop 0
	s_waitcnt lgkmcnt(2)
	v_mfma_f32_16x16x32_bf16 v[24:27], v[80:83], v[224:227], v[24:27]
	s_nop 0
	s_waitcnt lgkmcnt(1)
	v_mfma_f32_16x16x32_bf16 v[76:79], v[76:79], v[228:231], v[24:27]
	s_nop 7
	v_cvt_pk_bf16_f32 v24, v76, v77
	v_cvt_pk_bf16_f32 v25, v78, v79
	ds_write_b64 v145, v[24:25] offset:4352
	s_setprio 0
	s_waitcnt lgkmcnt(0)
	s_barrier
	s_add_i32 s24, s45, 1
	s_cmp_ge_u32 s24, s43
	s_cbranch_scc1 .LBB0_133
	s_add_i32 s24, s45, 3
	s_min_u32 s24, s24, s44
	s_add_i32 s24, s24, s42
	s_mul_hi_u32 s25, s24, 0x12100
	s_mul_i32 s24, s24, 0x12100
	s_add_u32 s24, s37, s24
	s_addc_u32 s25, s39, s25
	s_add_u32 s26, s24, 0x8000
	s_addc_u32 s27, s25, 0
	s_add_u32 s46, s24, 0xc000
	v_mov_b32_e32 v99, v137
	v_lshl_add_u64 v[22:23], s[24:25], 0, v[106:107]
	s_addc_u32 s47, s25, 0
	v_lshl_add_u64 v[22:23], v[22:23], 0, v[98:99]
	v_lshl_add_u64 v[0:1], s[24:25], 0, v[102:103]
	v_lshl_add_u64 v[4:5], s[24:25], 0, v[104:105]
	v_lshl_add_u64 v[6:7], s[26:27], 0, v[102:103]
	v_lshl_add_u64 v[12:13], s[26:27], 0, v[104:105]
	v_lshl_add_u64 v[14:15], s[46:47], 0, v[106:107]
	v_lshl_add_u64 v[20:21], v[84:85], 1, s[46:47]
	v_add_co_u32_e32 v24, vcc, s97, v22
	v_lshl_add_u64 v[0:1], v[0:1], 0, v[136:137]
	v_lshl_add_u64 v[4:5], v[4:5], 0, v[136:137]
	v_lshl_add_u64 v[8:9], v[6:7], 0, v[136:137]
	v_lshl_add_u64 v[12:13], v[12:13], 0, v[136:137]
	v_lshl_add_u64 v[16:17], v[14:15], 0, v[98:99]
	v_lshl_add_u64 v[20:21], v[20:21], 0, v[98:99]
	v_addc_co_u32_e32 v25, vcc, 0, v23, vcc
	v_mov_b32_e32 v109, v137
	global_load_dword v148, v206, s[24:25]
	s_nop 0
	global_load_dwordx4 v[0:3], v[0:1], off
	s_nop 0
	global_load_dwordx4 v[4:7], v[4:5], off
	s_nop 0
	global_load_dwordx4 v[8:11], v[8:9], off
	s_nop 0
	global_load_dwordx4 v[12:15], v[12:13], off
	s_nop 0
	global_load_dwordx4 v[16:19], v[16:17], off
	s_nop 0
	global_load_dwordx4 v[20:23], v[20:21], off
	s_nop 0
	global_load_dwordx4 v[28:31], v[24:25], off
	v_lshl_add_u64 v[24:25], s[24:25], 0, v[108:109]
	v_lshl_add_u64 v[24:25], v[24:25], 0, v[98:99]
	v_add_co_u32_e32 v24, vcc, s93, v24
	s_nop 1
	v_addc_co_u32_e32 v25, vcc, 0, v25, vcc
	global_load_dwordx4 v[32:35], v[24:25], off
	ds_read_b128 v[24:27], v135
	ds_read_b128 v[36:39], v135 offset:64
	ds_read_b128 v[150:153], v138
	ds_read_b128 v[154:157], v138 offset:64
	ds_read_b128 v[80:83], v135 offset:128
	ds_read_b128 v[158:161], v135 offset:192
	ds_read_b128 v[162:165], v138 offset:128
	ds_read_b128 v[166:169], v138 offset:192
	ds_read_b64 v[170:171], v139
	s_setprio 1
	s_waitcnt lgkmcnt(6)
	v_mfma_f32_16x16x32_bf16 v[24:27], v[24:27], v[150:153], 0
	s_waitcnt lgkmcnt(5)
	v_mfma_f32_16x16x32_bf16 v[24:27], v[36:39], v[154:157], v[24:27]
	s_waitcnt lgkmcnt(0)
	v_lshlrev_b32_e32 v36, 16, v170
	v_and_b32_e32 v37, 0xffff0000, v170
	v_lshlrev_b32_e32 v38, 16, v171
	v_mfma_f32_16x16x32_bf16 v[24:27], v[80:83], v[162:165], v[24:27]
	v_and_b32_e32 v39, 0xffff0000, v171
	v_mfma_f32_16x16x32_bf16 v[24:27], v[158:161], v[166:169], v[24:27]
	s_nop 7
	v_pk_add_f32 v[24:25], v[36:37], v[24:25] neg_lo:[0,1] neg_hi:[0,1]
	v_pk_add_f32 v[26:27], v[38:39], v[26:27] neg_lo:[0,1] neg_hi:[0,1]
	v_cvt_pk_bf16_f32 v24, v24, v25
	v_cvt_pk_bf16_f32 v25, v26, v27
	ds_write_b64 v124, v[24:25]
	ds_read_b128 v[24:27], v146
	ds_read_b128 v[158:161], v146 offset:64
	ds_read_b128 v[170:173], v146 offset:128
	ds_read_b128 v[174:177], v146 offset:192
	ds_read_b128 v[190:193], v140
	ds_read_b128 v[194:197], v140 offset:64
	ds_read_b128 v[80:83], v141
	ds_read_b128 v[36:39], v141 offset:64
	s_setprio 0
	s_waitcnt lgkmcnt(0)
	s_barrier
	s_waitcnt vmcnt(16)
	ds_write_b128 v115, v[40:43]
	s_waitcnt vmcnt(15)
	ds_write_b128 v116, v[44:47]
	s_waitcnt vmcnt(14)
	ds_write_b128 v115, v[48:51] offset:17408
	s_waitcnt vmcnt(13)
	ds_write_b128 v116, v[52:55] offset:17408
	s_waitcnt vmcnt(12)
	ds_write_b128 v117, v[56:59] offset:34816
	s_waitcnt vmcnt(11)
	ds_write_b128 v118, v[60:63] offset:34816
	s_waitcnt vmcnt(10)
	ds_write_b128 v117, v[64:67] offset:53248
	s_and_saveexec_b64 s[24:25], s[4:5]
	s_cbranch_execz .LBB0_156
	s_waitcnt vmcnt(9)
	ds_write_b128 v117, v[68:71] offset:62464
.LBB0_156:
	s_or_b64 exec, exec, s[24:25]
	s_setprio 1
	s_waitcnt lgkmcnt(7)
	v_mfma_f32_16x16x32_bf16 v[24:27], v[24:27], v[150:153], 0
	s_waitcnt lgkmcnt(6)
	v_mfma_f32_16x16x32_bf16 v[24:27], v[158:161], v[154:157], v[24:27]
	ds_read_b128 v[150:153], v149
	ds_read_b128 v[154:157], v149 offset:64
	ds_read_b128 v[216:219], v147
	ds_read_b128 v[220:223], v147 offset:64
	ds_read_b128 v[224:227], v147 offset:2304
	ds_read_b128 v[228:231], v147 offset:2368
	s_waitcnt lgkmcnt(7)
	v_mfma_f32_16x16x32_bf16 v[24:27], v[170:173], v[162:165], v[24:27]
	s_waitcnt lgkmcnt(6)
	v_mfma_f32_16x16x32_bf16 v[24:27], v[174:177], v[166:169], v[24:27]
	s_waitcnt lgkmcnt(5)
	v_mfma_f32_16x16x32_bf16 v[24:27], v[190:193], v[150:153], v[24:27]
	s_waitcnt lgkmcnt(4)
	v_mfma_f32_16x16x32_bf16 v[24:27], v[194:197], v[154:157], v[24:27]
	s_and_saveexec_b64 s[24:25], s[6:7]
	s_cbranch_execz .LBB0_150
	s_nop 5
	v_cvt_pk_bf16_f32 v24, v24, s0
	global_store_short v[110:111], v24, off
	s_or_b64 exec, exec, s[24:25]
	s_and_saveexec_b64 s[24:25], s[8:9]
	s_cbranch_execnz .LBB0_151

; #define LDS_BARRIER() do { asm volatile("s_waitcnt lgkmcnt(0)" ::: "memory"); __builtin_amdgcn_s_barrier(); asm volatile("" ::: "memory"); } while (0)
; __device__ __forceinline__ void g2_phase(unsigned char* lds, const Params& p, int l, int hf, const int tid) {
;     ...
;         int cur = 0;
;         G2_LOADR(0, rA, glA); G2_LOADR(1, rB, glB);
;         G2_STORER(0, rA);
;         float gl0 = glA;
;         G2_LOADR(2, rA, glA);
;         LDS_BARRIER();
;         float glcur = gl0, glnext = glB, glnn = glA;
;         for (int step = 0; step < nsteps; step += 2) {
;             { float gtmp; G2_STEP(step, 0, glcur, rB, gtmp); glcur = glnext; glnext = glnn; glnn = gtmp; }
;             if (step + 1 >= nsteps) break;
;             { float gtmp; G2_STEP(step + 1, 1, glcur, rA, gtmp); glcur = glnext; glnext = glnn; glnn = gtmp; }
.LBB0_154:
	s_or_b64 exec, exec, s[24:25]
	s_nop 0
	v_pk_mul_f32 v[26:27], v[112:113], v[74:75] op_sel_hi:[0,1]
	v_pk_mul_f32 v[24:25], v[112:113], v[72:73] op_sel_hi:[0,1]
	s_waitcnt lgkmcnt(3)
	s_nop 0
	v_mfma_f32_16x16x32_bf16 v[24:27], v[80:83], v[216:219], v[24:27]
	s_nop 0
	s_waitcnt lgkmcnt(2)
	v_mfma_f32_16x16x32_bf16 v[24:27], v[36:39], v[220:223], v[24:27]
	v_mul_f32_e64 v152, v112, v78
	v_mul_f32_e64 v153, v112, v79
	s_nop 5
	v_cvt_pk_bf16_f32 v150, v24, v25
	v_cvt_pk_bf16_f32 v151, v26, v27
	ds_write_b64 v87, v[150:151]
	s_nop 0
	v_pk_mul_f32 v[150:151], v[112:113], v[76:77] op_sel_hi:[0,1]
	s_waitcnt lgkmcnt(2)
	s_nop 0
	v_mfma_f32_16x16x32_bf16 v[80:83], v[80:83], v[224:227], v[150:153]
	s_nop 2
	s_nop 0
	s_waitcnt lgkmcnt(1)
	v_mfma_f32_16x16x32_bf16 v[36:39], v[36:39], v[228:231], v[80:83]
	s_nop 7
	v_cvt_pk_bf16_f32 v80, v36, v37
	v_cvt_pk_bf16_f32 v81, v38, v39
	ds_write_b64 v87, v[80:81] offset:4352
	s_setprio 0
	s_add_i32 s24, s45, 4
	s_min_u32 s24, s24, s44
	s_add_i32 s24, s24, s42
	s_mul_hi_u32 s25, s24, 0x12100
	s_mul_i32 s24, s24, 0x12100
	s_add_u32 s24, s37, s24
	s_addc_u32 s25, s39, s25
	s_add_u32 s26, s24, 0x8000
	s_addc_u32 s27, s25, 0
	v_mov_b32_e32 v99, v137
	v_lshl_add_u64 v[62:63], s[24:25], 0, v[106:107]
	s_add_u32 s46, s24, 0xc000
	v_lshl_add_u64 v[62:63], v[62:63], 0, v[98:99]
	v_mov_b32_e32 v109, v137
	s_addc_u32 s47, s25, 0
	v_add_co_u32_e32 v64, vcc, s97, v62
	s_waitcnt vmcnt(9)
	v_lshl_add_u64 v[68:69], s[24:25], 0, v[108:109]
	v_lshl_add_u64 v[40:41], s[24:25], 0, v[102:103]
	v_lshl_add_u64 v[44:45], s[24:25], 0, v[104:105]
	v_lshl_add_u64 v[46:47], s[26:27], 0, v[102:103]
	v_lshl_add_u64 v[52:53], s[26:27], 0, v[104:105]
	v_lshl_add_u64 v[54:55], s[46:47], 0, v[106:107]
	v_lshl_add_u64 v[60:61], v[84:85], 1, s[46:47]
	v_addc_co_u32_e32 v65, vcc, 0, v63, vcc
	v_lshl_add_u64 v[68:69], v[68:69], 0, v[98:99]
	s_waitcnt lgkmcnt(0)
	s_barrier
	v_lshl_add_u64 v[40:41], v[40:41], 0, v[136:137]
	v_lshl_add_u64 v[44:45], v[44:45], 0, v[136:137]
	v_lshl_add_u64 v[48:49], v[46:47], 0, v[136:137]
	v_lshl_add_u64 v[52:53], v[52:53], 0, v[136:137]
	v_lshl_add_u64 v[56:57], v[54:55], 0, v[98:99]
	v_lshl_add_u64 v[60:61], v[60:61], 0, v[98:99]
	v_add_co_u32_e32 v68, vcc, s93, v68
	global_load_dword v80, v206, s[24:25]
	s_nop 0
	global_load_dwordx4 v[40:43], v[40:41], off
	s_nop 0
	global_load_dwordx4 v[44:47], v[44:45], off
	s_nop 0
	global_load_dwordx4 v[48:51], v[48:49], off
	s_nop 0
	global_load_dwordx4 v[52:55], v[52:53], off
	s_nop 0
	global_load_dwordx4 v[56:59], v[56:57], off
	s_nop 0
	global_load_dwordx4 v[60:63], v[60:61], off
	s_nop 0
	global_load_dwordx4 v[64:67], v[64:65], off
	v_addc_co_u32_e32 v69, vcc, 0, v69, vcc
	global_load_dwordx4 v[68:71], v[68:69], off
	s_add_i32 s45, s45, 2
	s_mov_b64 s[24:25], 0x2000
	s_cmp_ge_u32 s45, s43
	v_lshl_add_u64 v[110:111], v[110:111], 0, s[24:25]
	s_mov_b64 s[24:25], 0
	s_cselect_b64 s[26:27], -1, 0
	s_and_b64 vcc, exec, s[26:27]
	s_cbranch_vccz .LBB0_134
